# RWKV: waves 4-7 L2-prefetch only the next group's phase-A prologue rows (first 8 rows of each chunk) (on v52)
# speedup vs baseline: 1.0136x; 1.0136x over previous
; __device__ __forceinline__ float bf2f(bf16_t v) { return __uint_as_float(((unsigned)v) << 16); }
; __device__ __forceinline__ void rwkv_phaseA(const Ctx& F, LAS unsigned char* W, unsigned char* X, int b, int h, int c) {
;     ...
;         const size_t row0 = (size_t)b * S + c * 32;
;         const bf16_t* pb = proj + row0 * IN_EVEN_P + RW_OFF + h * 64; const bf16_t* lb = LO + row0 * 1536 + h * 64;
;         float pr_ = 0.f, pk_ = 0.f, pv_ = 0.f;
;         if (c > 0) { const bf16_t* pp = pb - IN_EVEN_P; pr_ = bf2f(pp[ul0]); pk_ = bf2f(pp[512 + ul0]); pv_ = bf2f(pp[1024 + ul0]); }
;         bf16_t cur[8][5], nxt[8][5];
; __device__ __forceinline__ void rwkv_chunked_bh(const Ctx& F, int b, int h) {
;     ...
;     for (int grp = 0; grp < S / 32 / RG; ++grp) {
;         __syncthreads();
;         if (w < RG) rwkv_phaseA(F, L + w * RA_BYTES, XS + w * RX_BYTES, b, h, grp * RG + w);
.Lrw_pf:
	s_sub_i32 s32, s50, 4
	s_lshl_b32 s32, s32, 6
	v_add_u32_e32 v150, s32, v71
	v_and_b32_e32 v152, 7, v150
	v_lshrrev_b32_e32 v151, 3, v150
	s_lshl_b32 s32, s22, 7
	s_add_u32 s32, s38, s32
	s_movk_i32 s100, 0x1400
	s_movk_i32 s101, 0xc00
	v_add_u32_e32 v153, s32, v151
	v_cmp_lt_u32_e32 vcc, 5, v152
	v_lshrrev_b32_e32 v156, 1, v152
	v_and_b32_e32 v158, 1, v152
	v_lshlrev_b32_e32 v156, 10, v156
	v_lshl_add_u32 v154, v158, 6, v156
	v_lshlrev_b32_e32 v156, 10, v158
	v_mul_lo_u32 v159, v153, s100
	v_mul_lo_u32 v153, v153, s101
	s_lshl_b32 s32, s14, 1
	s_add_u32 s32, s32, 0xc200540
	v_add3_u32 v154, v159, v154, s32
	v_add_u32_e32 v156, v153, v156
	v_mov_b32_e32 v155, 0
	v_mov_b32_e32 v157, 0
	s_mov_b32 s98, s15
	s_mov_b32 s99, s70
	v_lshl_add_u64 v[160:161], s[46:47], 0, v[154:155]
	v_lshl_add_u64 v[162:163], s[98:99], 0, v[156:157]
	v_mov_b32_e32 v166, 0x28000
	v_mov_b32_e32 v167, 0x18000
	v_cndmask_b32_e32 v160, v160, v162, vcc
	v_cndmask_b32_e32 v161, v161, v163, vcc
	v_cndmask_b32_e32 v164, v166, v167, vcc
	v_mov_b32_e32 v165, 0
	v_mov_b32_e32 v166, 0x1400
	v_mov_b32_e32 v167, 0xc00
	v_cndmask_b32_e32 v166, v166, v167, vcc
	v_mov_b64_e32 v[168:169], v[160:161]
	s_cmp_eq_u32 s22, 15
	s_cbranch_scc1 .LBB0_833
	v_lshrrev_b32_e32 v162, 6, v150
	v_mul_u32_u24_e32 v162, 24, v162
	v_add_u32_e32 v162, 0x80, v162
	v_mul_u32_u24_e32 v162, v162, v166
	v_mov_b32_e32 v163, 0
	v_lshl_add_u64 v[168:169], v[168:169], 0, v[162:163]
	global_load_dword v174, v[168:169], off
